# speedup vs baseline: 1.0288x; 1.0288x over previous
.LBB0_371:
	s_and_b64 s[0:1], s[6:7], exec
	s_cselect_b32 s0, s16, s10
	s_barrier
	v_add_u32_e32 v2, s0, v0
	v_ashrrev_i32_e32 v3, 31, v2
	v_lshl_add_u64 v[4:5], v[2:3], 2, s[26:27]
	v_add_u32_e32 v2, 0x400, v2
	global_load_dword v80, v[4:5], off
	v_ashrrev_i32_e32 v3, 31, v2
	v_lshl_add_u64 v[2:3], v[2:3], 2, s[26:27]
	global_load_dword v81, v[2:3], off
	s_waitcnt vmcnt(0)
	ds_write_b32 v0, v80 offset:4096
	ds_write_b32 v0, v81 offset:5120
	s_waitcnt lgkmcnt(0)
	s_barrier
	s_and_saveexec_b64 s[12:13], s[38:39]
	s_cbranch_execz .LBB0_375
	s_mov_b32 s1, 0
	v_mov_b32_e32 v2, 0
.Lscan_mchain:
	v_mov_b32_e32 v6, s1
	ds_read_b128 v[58:61], v6 offset:4096
	ds_read_b128 v[66:69], v6 offset:5120
	ds_read_b128 v[62:65], v6 offset:4112
	ds_read_b128 v[70:73], v6 offset:5136
	s_waitcnt lgkmcnt(2)
	v_add_f32_e32 v3, v2, v58
	v_max_f32_e32 v66, v66, v66
	v_max_f32_e32 v3, v3, v66
	v_add_f32_e32 v4, v3, v59
	v_max_f32_e32 v67, v67, v67
	v_max_f32_e32 v4, v4, v67
	v_add_f32_e32 v5, v4, v60
	v_max_f32_e32 v68, v68, v68
	v_max_f32_e32 v5, v5, v68
	ds_write_b128 v6, v[2:5]
	v_add_f32_e32 v74, v5, v61
	v_max_f32_e32 v69, v69, v69
	v_max_f32_e32 v74, v74, v69
	s_waitcnt lgkmcnt(1)
	v_add_f32_e32 v75, v74, v62
	v_max_f32_e32 v70, v70, v70
	v_max_f32_e32 v75, v75, v70
	v_add_f32_e32 v76, v75, v63
	v_max_f32_e32 v71, v71, v71
	v_max_f32_e32 v76, v76, v71
	v_add_f32_e32 v77, v76, v64
	v_max_f32_e32 v72, v72, v72
	v_max_f32_e32 v77, v77, v72
	ds_write_b128 v6, v[74:77] offset:16
	v_add_f32_e32 v2, v77, v65
	v_max_f32_e32 v73, v73, v73
	v_max_f32_e32 v2, v2, v73
	s_add_i32 s1, s1, 32
	s_cmpk_eq_i32 s1, 0x400
	s_cbranch_scc0 .Lscan_mchain
	ds_write_b32 v1, v2 offset:1024
.LBB0_375:
	s_or_b64 exec, exec, s[12:13]
	s_waitcnt lgkmcnt(0)
	s_barrier
	v_mov_b32_e32 v4, v80
	v_mov_b32_e32 v5, v81
	ds_read2_b32 v[2:3], v0 offset1:1
	s_andn2_b64 vcc, exec, s[8:9]
	s_waitcnt vmcnt(1) lgkmcnt(0)
	v_add_f32_e32 v2, v2, v4
	v_sub_f32_e32 v2, v2, v3
	v_mul_f32_e32 v4, 0x3fb8aa3b, v2
	s_waitcnt vmcnt(0)
	v_sub_f32_e32 v3, v5, v3
	v_mul_f32_e32 v5, 0x3fb8aa3b, v3
	v_fma_f32 v6, v2, s74, -v4
	v_rndne_f32_e32 v7, v4
	v_fma_f32 v8, v3, s74, -v5
	v_rndne_f32_e32 v9, v5
	v_fmac_f32_e32 v6, 0x32a5705f, v2
	v_sub_f32_e32 v4, v4, v7
	v_fmac_f32_e32 v8, 0x32a5705f, v3
	v_sub_f32_e32 v5, v5, v9
	v_add_f32_e32 v4, v4, v6
	v_cvt_i32_f32_e32 v7, v7
	v_add_f32_e32 v5, v5, v8
	v_exp_f32_e32 v4, v4
	v_cvt_i32_f32_e32 v9, v9
	v_exp_f32_e32 v5, v5
	v_cmp_ngt_f32_e64 s[0:1], s75, v2
	v_ldexp_f32 v4, v4, v7
	v_ldexp_f32 v5, v5, v9
	v_cndmask_b32_e64 v4, 0, v4, s[0:1]
	v_cmp_ngt_f32_e64 s[0:1], s75, v3
	s_nop 1
	v_cndmask_b32_e64 v5, 0, v5, s[0:1]
	v_cmp_nlt_f32_e64 s[0:1], s19, v2
	s_nop 1
	v_cndmask_b32_e64 v2, v172, v4, s[0:1]
	v_cmp_nlt_f32_e64 s[0:1], s19, v3
	s_nop 1
	v_cndmask_b32_e64 v3, v172, v5, s[0:1]
	s_mov_b64 s[0:1], -1
	ds_write_b32 v0, v2 offset:1040
	ds_write_b32 v0, v3 offset:2080
	s_waitcnt lgkmcnt(0)
	s_barrier
	s_cbranch_vccnz .LBB0_379
	v_mov_b32_e32 v30, 0
	s_movk_i32 s0, 0x410
	s_mov_b32 s1, -8
	v_mov_b64_e32 v[14:15], v[10:11]
	v_mov_b32_e32 v31, v30
	v_mov_b32_e32 v18, v30
	v_mov_b32_e32 v19, v30
.LBB0_377:
	s_mov_b32 s35, -1
	s_mov_b32 s34, 0xfbea0000
	v_lshl_add_u64 v[58:59], v[14:15], 0, s[34:35]
	global_load_dwordx2 v[58:59], v[58:59], off offset:-4
	s_mov_b32 s34, 0xfbec0000
	v_lshl_add_u64 v[60:61], v[14:15], 0, s[34:35]
	global_load_dwordx2 v[60:61], v[60:61], off offset:-4
	s_mov_b32 s34, 0xfbee0000
	v_lshl_add_u64 v[62:63], v[14:15], 0, s[34:35]
	global_load_dwordx2 v[62:63], v[62:63], off offset:-4
	s_mov_b32 s34, 0xfbf00000
	v_lshl_add_u64 v[64:65], v[14:15], 0, s[34:35]
	global_load_dwordx2 v[64:65], v[64:65], off offset:-4
	s_mov_b32 s34, 0xfbf20000
	v_lshl_add_u64 v[66:67], v[14:15], 0, s[34:35]
	global_load_dwordx2 v[66:67], v[66:67], off offset:-4
	s_mov_b32 s34, 0xfbf40000
	v_lshl_add_u64 v[68:69], v[14:15], 0, s[34:35]
	global_load_dwordx2 v[68:69], v[68:69], off offset:-4
	s_mov_b32 s34, 0xfbf60000
	v_lshl_add_u64 v[70:71], v[14:15], 0, s[34:35]
	global_load_dwordx2 v[70:71], v[70:71], off offset:-4
	s_mov_b32 s34, 0xfbf80000
	v_lshl_add_u64 v[72:73], v[14:15], 0, s[34:35]
	global_load_dwordx2 v[72:73], v[72:73], off offset:-4
	v_pk_mov_b32 v[4:5], v[30:31], v[30:31] op_sel:[1,0]
	s_mov_b32 s11, 0xfff20000
	v_mov_b32_e32 v53, s0
	s_add_i32 s0, s0, 32
	s_add_i32 s1, s1, 8
	s_mov_b64 s[12:13], 0x100000
	s_waitcnt vmcnt(0)
	v_lshlrev_b32_e32 v42, 16, v58
	v_and_b32_e32 v43, 0xffff0000, v58
	v_lshlrev_b32_e32 v40, 16, v59
	v_and_b32_e32 v41, 0xffff0000, v59
	v_lshlrev_b32_e32 v48, 16, v60
	v_and_b32_e32 v49, 0xffff0000, v60
	v_lshlrev_b32_e32 v46, 16, v61
	v_and_b32_e32 v47, 0xffff0000, v61
	v_lshlrev_b32_e32 v25, 16, v62
	v_and_b32_e32 v24, 0xffff0000, v62
	v_lshlrev_b32_e32 v17, 16, v63
	v_and_b32_e32 v16, 0xffff0000, v63
	v_lshlrev_b32_e32 v29, 16, v64
	v_and_b32_e32 v28, 0xffff0000, v64
	v_lshlrev_b32_e32 v21, 16, v65
	v_and_b32_e32 v20, 0xffff0000, v65
	v_lshlrev_b32_e32 v35, 16, v66
	v_and_b32_e32 v34, 0xffff0000, v66
	v_lshlrev_b32_e32 v23, 16, v67
	v_and_b32_e32 v22, 0xffff0000, v67
	v_lshlrev_b32_e32 v39, 16, v68
	v_and_b32_e32 v38, 0xffff0000, v68
	v_lshlrev_b32_e32 v27, 16, v69
	v_and_b32_e32 v26, 0xffff0000, v69
	v_lshlrev_b32_e32 v45, 16, v70
	v_and_b32_e32 v44, 0xffff0000, v70
	v_lshlrev_b32_e32 v33, 16, v71
	v_and_b32_e32 v32, 0xffff0000, v71
	v_lshlrev_b32_e32 v51, 16, v72
	v_and_b32_e32 v50, 0xffff0000, v72
	v_lshlrev_b32_e32 v37, 16, v73
	v_and_b32_e32 v36, 0xffff0000, v73
	v_pk_mov_b32 v[2:3], v[18:19], v[18:19] op_sel:[1,0]
	s_nop 0
	v_cvt_pk_bf16_f32 v2, v2, v3
	v_cvt_pk_bf16_f32 v3, v4, v5
	v_add_co_u32_e32 v4, vcc, s11, v14
	s_mov_b32 s11, 0xfff40000
	s_nop 0
	v_addc_co_u32_e32 v5, vcc, -1, v15, vcc
	global_store_dwordx2 v[4:5], v[2:3], off offset:-4
	ds_read_b128 v[6:9], v53
	ds_read_b128 v[2:5], v53 offset:16
	ds_read_b128 v[54:57], v53 offset:1040
	s_waitcnt lgkmcnt(2)
	v_pk_mul_f32 v[18:19], v[18:19], v[6:7] op_sel_hi:[1,0]
	v_pk_mul_f32 v[30:31], v[30:31], v[6:7] op_sel_hi:[1,0]
	s_waitcnt lgkmcnt(0)
	v_pk_fma_f32 v[18:19], v[54:55], v[42:43], v[18:19] op_sel:[0,0,1] op_sel_hi:[0,1,0]
	v_pk_fma_f32 v[30:31], v[54:55], v[40:41], v[30:31] op_sel:[0,0,1] op_sel_hi:[0,1,0]
	v_add_co_u32_e32 v42, vcc, s11, v14
	v_cvt_pk_bf16_f32 v40, v18, v19
	v_cvt_pk_bf16_f32 v41, v30, v31
	v_addc_co_u32_e32 v43, vcc, -1, v15, vcc
	global_store_dwordx2 v[42:43], v[40:41], off offset:-4
	v_pk_mul_f32 v[40:41], v[54:55], v[48:49] op_sel:[1,0]
	s_mov_b32 s11, 0xfff60000
	v_pk_fma_f32 v[18:19], v[18:19], v[6:7], v[40:41] op_sel:[0,1,0]
	v_pk_mul_f32 v[40:41], v[54:55], v[46:47] op_sel:[1,0]
	v_mov_b32_e32 v46, v5
	v_pk_fma_f32 v[6:7], v[30:31], v[6:7], v[40:41] op_sel:[0,1,0]
	v_cvt_pk_bf16_f32 v30, v18, v19
	v_cvt_pk_bf16_f32 v31, v6, v7
	v_pk_mul_f32 v[18:19], v[18:19], v[8:9] op_sel_hi:[1,0]
	v_pk_mul_f32 v[6:7], v[6:7], v[8:9] op_sel_hi:[1,0]
	v_add_co_u32_e32 v40, vcc, s11, v14
	v_pk_fma_f32 v[18:19], v[56:57], v[24:25], v[18:19] op_sel:[0,0,1] op_sel_hi:[0,1,0]
	v_pk_fma_f32 v[6:7], v[56:57], v[16:17], v[6:7] op_sel:[0,0,1] op_sel_hi:[0,1,0]
	v_addc_co_u32_e32 v41, vcc, -1, v15, vcc
	v_pk_mov_b32 v[24:25], v[18:19], v[18:19] op_sel:[1,0]
	v_pk_mov_b32 v[16:17], v[6:7], v[6:7] op_sel:[1,0]
	s_mov_b32 s11, 0xfff80000
	v_cvt_pk_bf16_f32 v8, v24, v25
	v_mov_b32_e32 v24, v9
	v_cvt_pk_bf16_f32 v9, v16, v17
	v_add_co_u32_e32 v16, vcc, s11, v14
	global_store_dwordx2 v[40:41], v[30:31], off offset:-4
	v_mov_b32_e32 v30, v57
	v_addc_co_u32_e32 v17, vcc, -1, v15, vcc
	ds_read_b128 v[40:43], v53 offset:1056
	v_pk_mul_f32 v[28:29], v[30:31], v[28:29] op_sel_hi:[0,1]
	global_store_dwordx2 v[16:17], v[8:9], off offset:-4
	v_pk_mul_f32 v[8:9], v[30:31], v[20:21] op_sel_hi:[0,1]
	v_pk_fma_f32 v[18:19], v[18:19], v[24:25], v[28:29] op_sel_hi:[1,0,1]
	v_pk_fma_f32 v[6:7], v[6:7], v[24:25], v[8:9] op_sel_hi:[1,0,1]
	v_pk_mov_b32 v[28:29], v[18:19], v[18:19] op_sel:[1,0]
	v_pk_mov_b32 v[8:9], v[6:7], v[6:7] op_sel:[1,0]
	s_mov_b32 s11, 0xfffa0000
	v_cvt_pk_bf16_f32 v28, v28, v29
	v_cvt_pk_bf16_f32 v29, v8, v9
	v_add_co_u32_e32 v8, vcc, s11, v14
	s_waitcnt lgkmcnt(0)
	v_pk_mul_f32 v[34:35], v[40:41], v[34:35] op_sel_hi:[0,1]
	v_addc_co_u32_e32 v9, vcc, -1, v15, vcc
	global_store_dwordx2 v[8:9], v[28:29], off offset:-4
	v_pk_mul_f32 v[8:9], v[40:41], v[22:23] op_sel_hi:[0,1]
	v_pk_fma_f32 v[18:19], v[18:19], v[2:3], v[34:35] op_sel_hi:[1,0,1]
	v_pk_fma_f32 v[6:7], v[6:7], v[2:3], v[8:9] op_sel_hi:[1,0,1]
	v_pk_mov_b32 v[34:35], v[18:19], v[18:19] op_sel:[1,0]
	v_pk_mov_b32 v[8:9], v[6:7], v[6:7] op_sel:[1,0]
	s_mov_b32 s11, 0xfffc0000
	v_cvt_pk_bf16_f32 v34, v34, v35
	v_cvt_pk_bf16_f32 v35, v8, v9
	v_add_co_u32_e32 v8, vcc, s11, v14
	v_pk_mul_f32 v[38:39], v[40:41], v[38:39] op_sel:[1,0]
	s_nop 0
	v_addc_co_u32_e32 v9, vcc, -1, v15, vcc
	global_store_dwordx2 v[8:9], v[34:35], off offset:-4
	v_pk_mul_f32 v[8:9], v[40:41], v[26:27] op_sel:[1,0]
	v_pk_fma_f32 v[18:19], v[18:19], v[2:3], v[38:39] op_sel:[0,1,0]
	v_pk_fma_f32 v[2:3], v[6:7], v[2:3], v[8:9] op_sel:[0,1,0]
	v_pk_mov_b32 v[38:39], v[18:19], v[18:19] op_sel:[1,0]
	v_pk_mov_b32 v[6:7], v[2:3], v[2:3] op_sel:[1,0]
	s_mov_b32 s11, 0xfffe0000
	v_cvt_pk_bf16_f32 v38, v38, v39
	v_cvt_pk_bf16_f32 v39, v6, v7
	v_add_co_u32_e32 v6, vcc, s11, v14
	v_pk_mul_f32 v[44:45], v[42:43], v[44:45] op_sel_hi:[0,1]
	s_nop 0
	v_addc_co_u32_e32 v7, vcc, -1, v15, vcc
	global_store_dwordx2 v[6:7], v[38:39], off offset:-4
	v_pk_mul_f32 v[6:7], v[42:43], v[32:33] op_sel_hi:[0,1]
	v_pk_fma_f32 v[18:19], v[18:19], v[4:5], v[44:45] op_sel_hi:[1,0,1]
	v_pk_fma_f32 v[2:3], v[2:3], v[4:5], v[6:7] op_sel_hi:[1,0,1]
	v_pk_mov_b32 v[44:45], v[18:19], v[18:19] op_sel:[1,0]
	v_mov_b32_e32 v48, v43
	v_pk_mov_b32 v[4:5], v[2:3], v[2:3] op_sel:[1,0]
	v_cvt_pk_bf16_f32 v44, v44, v45
	v_pk_mul_f32 v[50:51], v[48:49], v[50:51] op_sel_hi:[0,1]
	v_cvt_pk_bf16_f32 v45, v4, v5
	v_pk_mul_f32 v[4:5], v[48:49], v[36:37] op_sel_hi:[0,1]
	v_pk_fma_f32 v[18:19], v[18:19], v[46:47], v[50:51] op_sel_hi:[1,0,1]
	global_store_dwordx2 v[14:15], v[44:45], off offset:-4
	v_pk_fma_f32 v[30:31], v[2:3], v[46:47], v[4:5] op_sel_hi:[1,0,1]
	v_lshl_add_u64 v[14:15], v[14:15], 0, s[12:13]
	s_cmpk_gt_u32 s1, 0xf7
	s_cbranch_scc0 .LBB0_377
	s_mov_b64 s[0:1], 0

.LBB0_382:
	v_lshl_add_u64 v[8:9], v[12:13], 0, s[12:13]
	s_mov_b32 s35, 0
	s_mov_b32 s34, 0x2ef01000
	v_lshl_add_u64 v[106:107], v[8:9], 0, s[34:35]
	s_mov_b32 s34, 0x2ef03000
	v_lshl_add_u64 v[108:109], v[8:9], 0, s[34:35]
	s_mov_b32 s34, 0x2ef05000
	v_lshl_add_u64 v[110:111], v[8:9], 0, s[34:35]
	s_mov_b32 s34, 0x2ef07000
	v_lshl_add_u64 v[112:113], v[8:9], 0, s[34:35]
	global_load_dword v58, v[106:107], off offset:-4096
	global_load_dword v59, v[106:107], off offset:-2048
	global_load_dword v60, v[106:107], off
	global_load_dword v61, v[106:107], off offset:2048
	global_load_dword v62, v[108:109], off offset:-4096
	global_load_dword v63, v[108:109], off offset:-2048
	global_load_dword v64, v[108:109], off
	global_load_dword v65, v[108:109], off offset:2048
	global_load_dword v66, v[110:111], off offset:-4096
	global_load_dword v67, v[110:111], off offset:-2048
	global_load_dword v68, v[110:111], off
	global_load_dword v69, v[110:111], off offset:2048
	global_load_dword v70, v[112:113], off offset:-4096
	global_load_dword v71, v[112:113], off offset:-2048
	global_load_dword v72, v[112:113], off
	global_load_dword v73, v[112:113], off offset:2048
	v_mov_b32_e32 v28, s11
	ds_read_b128 v[74:77], v28
	ds_read_b128 v[90:93], v28 offset:1040
	ds_read_b128 v[78:81], v28 offset:16
	ds_read_b128 v[94:97], v28 offset:1056
	ds_read_b128 v[82:85], v28 offset:32
	ds_read_b128 v[98:101], v28 offset:1072
	ds_read_b128 v[86:89], v28 offset:48
	ds_read_b128 v[102:105], v28 offset:1088
	s_mov_b32 s34, 0x30f81000
	v_lshl_add_u64 v[114:115], v[8:9], 0, s[34:35]
	s_mov_b32 s34, 0x30f83000
	v_lshl_add_u64 v[116:117], v[8:9], 0, s[34:35]
	s_mov_b32 s34, 0x30f85000
	v_lshl_add_u64 v[118:119], v[8:9], 0, s[34:35]
	s_mov_b32 s34, 0x30f87000
	v_lshl_add_u64 v[120:121], v[8:9], 0, s[34:35]
	global_store_dword v[114:115], v2, off offset:-4096
	s_add_i32 s11, s11, 64
	s_add_u32 s12, s12, 0x8000
	s_addc_u32 s13, s13, 0
	s_waitcnt vmcnt(1) lgkmcnt(0)
	v_mul_f32_e32 v58, v90, v58
	v_fmac_f32_e32 v58, v2, v74
	global_store_dword v[114:115], v58, off offset:-2048
	v_mul_f32_e32 v59, v91, v59
	v_fmac_f32_e32 v59, v58, v75
	global_store_dword v[114:115], v59, off
	v_mul_f32_e32 v60, v92, v60
	v_fmac_f32_e32 v60, v59, v76
	global_store_dword v[114:115], v60, off offset:2048
	v_mul_f32_e32 v61, v93, v61
	v_fmac_f32_e32 v61, v60, v77
	global_store_dword v[116:117], v61, off offset:-4096
	v_mul_f32_e32 v62, v94, v62
	v_fmac_f32_e32 v62, v61, v78
	global_store_dword v[116:117], v62, off offset:-2048
	v_mul_f32_e32 v63, v95, v63
	v_fmac_f32_e32 v63, v62, v79
	global_store_dword v[116:117], v63, off
	v_mul_f32_e32 v64, v96, v64
	v_fmac_f32_e32 v64, v63, v80
	global_store_dword v[116:117], v64, off offset:2048
	v_mul_f32_e32 v65, v97, v65
	v_fmac_f32_e32 v65, v64, v81
	global_store_dword v[118:119], v65, off offset:-4096
	v_mul_f32_e32 v66, v98, v66
	v_fmac_f32_e32 v66, v65, v82
	global_store_dword v[118:119], v66, off offset:-2048
	v_mul_f32_e32 v67, v99, v67
	v_fmac_f32_e32 v67, v66, v83
	global_store_dword v[118:119], v67, off
	v_mul_f32_e32 v68, v100, v68
	v_fmac_f32_e32 v68, v67, v84
	global_store_dword v[118:119], v68, off offset:2048
	v_mul_f32_e32 v69, v101, v69
	v_fmac_f32_e32 v69, v68, v85
	global_store_dword v[120:121], v69, off offset:-4096
	v_mul_f32_e32 v70, v102, v70
	v_fmac_f32_e32 v70, v69, v86
	global_store_dword v[120:121], v70, off offset:-2048
	v_mul_f32_e32 v71, v103, v71
	v_fmac_f32_e32 v71, v70, v87
	global_store_dword v[120:121], v71, off
	v_mul_f32_e32 v72, v104, v72
	v_fmac_f32_e32 v72, v71, v88
	global_store_dword v[120:121], v72, off offset:2048
	v_mul_f32_e32 v2, v105, v73
	v_fmac_f32_e32 v2, v72, v89
	s_cmp_lg_u32 s12, 0x80000
	s_cbranch_scc1 .LBB0_382
	s_branch .LBB0_369

.LBB0_479:
	v_ashrrev_i32_e32 v151, 31, v150
	v_mov_b32_e32 v31, 0
	s_andn2_b64 vcc, exec, s[0:1]
	v_mov_b32_e32 v30, 0
	v_mov_b32_e32 v29, 0
	v_mov_b32_e32 v28, 0
	v_mov_b32_e32 v27, 0
	v_mov_b32_e32 v26, 0
	v_mov_b32_e32 v25, 0
	v_mov_b32_e32 v24, 0
	v_mov_b32_e32 v23, 0
	v_mov_b32_e32 v22, 0
	v_mov_b32_e32 v21, 0
	v_mov_b32_e32 v20, 0
	v_mov_b32_e32 v19, 0
	v_mov_b32_e32 v18, 0
	v_mov_b32_e32 v17, 0
	v_mov_b32_e32 v16, 0
	v_mov_b32_e32 v47, 0
	v_mov_b32_e32 v46, 0
	v_mov_b32_e32 v45, 0
	v_mov_b32_e32 v44, 0
	v_mov_b32_e32 v43, 0
	v_mov_b32_e32 v42, 0
	v_mov_b32_e32 v41, 0
	v_mov_b32_e32 v40, 0
	v_mov_b32_e32 v39, 0
	v_mov_b32_e32 v38, 0
	v_mov_b32_e32 v37, 0
	v_mov_b32_e32 v36, 0
	v_mov_b32_e32 v35, 0
	v_mov_b32_e32 v34, 0
	v_mov_b32_e32 v33, 0
	v_mov_b32_e32 v32, 0
	v_mov_b32_e32 v190, 0
	s_cbranch_vccnz .LBB0_390
	v_lshrrev_b32_e32 v0, 2, v2
	v_lshlrev_b64 v[16:17], 3, v[2:3]
	v_lshlrev_b64 v[18:19], 3, v[4:5]
	v_lshlrev_b32_e32 v2, 1, v2
	v_and_b32_e32 v3, 24, v8
	v_and_or_b32 v0, v0, 3, v189
	v_mov_b32_e32 v14, v1
	v_mov_b32_e32 v15, v1
	v_lshlrev_b64 v[152:153], 3, v[6:7]
	v_and_or_b32 v191, v2, 32, v3
	v_mul_u32_u24_e32 v192, 0xc0, v0
	v_mov_b32_e32 v0, v1
	v_mov_b32_e32 v2, v1
	v_mov_b32_e32 v3, v1
	v_mov_b32_e32 v4, v1
	v_mov_b32_e32 v5, v1
	v_mov_b32_e32 v6, v1
	v_mov_b32_e32 v7, v1
	v_mov_b32_e32 v8, v1
	v_mov_b32_e32 v9, v1
	v_mov_b32_e32 v10, v1
	v_mov_b32_e32 v11, v1
	v_mov_b32_e32 v12, v1
	v_mov_b32_e32 v13, v1
	v_lshlrev_b64 v[154:155], 1, v[16:17]
	v_lshlrev_b64 v[156:157], 1, v[18:19]
	v_mov_b64_e32 v[30:31], v[14:15]
	v_mov_b64_e32 v[46:47], v[14:15]
	v_mov_b64_e32 v[110:111], v[14:15]
	v_mov_b64_e32 v[94:95], v[14:15]
	s_or_b32 s35, s14, 31
	s_mov_b32 s40, 3
	v_mov_b32_e32 v193, 0xff800000
	v_mov_b32_e32 v190, 0
	s_movk_i32 s41, 0x7f
	v_mov_b64_e32 v[28:29], v[12:13]
	v_mov_b64_e32 v[26:27], v[10:11]
	v_mov_b64_e32 v[24:25], v[8:9]
	v_mov_b64_e32 v[22:23], v[6:7]
	v_mov_b64_e32 v[20:21], v[4:5]
	v_mov_b64_e32 v[18:19], v[2:3]
	v_mov_b64_e32 v[16:17], v[0:1]
	v_mov_b64_e32 v[44:45], v[12:13]
	v_mov_b64_e32 v[42:43], v[10:11]
	v_mov_b64_e32 v[40:41], v[8:9]
	v_mov_b64_e32 v[38:39], v[6:7]
	v_mov_b64_e32 v[36:37], v[4:5]
	v_mov_b64_e32 v[34:35], v[2:3]
	v_mov_b64_e32 v[32:33], v[0:1]
	v_mov_b64_e32 v[108:109], v[12:13]
	v_mov_b64_e32 v[106:107], v[10:11]
	v_mov_b64_e32 v[104:105], v[8:9]
	v_mov_b64_e32 v[102:103], v[6:7]
	v_mov_b64_e32 v[100:101], v[4:5]
	v_mov_b64_e32 v[98:99], v[2:3]
	v_mov_b64_e32 v[96:97], v[0:1]
	v_mov_b64_e32 v[92:93], v[12:13]
	v_mov_b64_e32 v[90:91], v[10:11]
	v_mov_b64_e32 v[88:89], v[8:9]
	v_mov_b64_e32 v[86:87], v[6:7]
	v_mov_b64_e32 v[84:85], v[4:5]
	v_mov_b64_e32 v[82:83], v[2:3]
	v_mov_b64_e32 v[80:81], v[0:1]
	s_cmp_gt_i32 s15, 2
	s_cselect_b32 s100, 2, 0
	s_mul_hi_u32 s47, s100, 0x3000
	s_mul_i32 s46, s100, 0x3000
	s_add_u32 s46, s6, s46
	s_addc_u32 s47, s7, s47
	s_add_u32 s48, s8, 0x2000
	s_addc_u32 s49, s9, 0
	v_lshl_add_u64 v[210:211], s[46:47], 0, v[154:155]
	v_lshl_add_u64 v[214:215], s[46:47], 0, v[156:157]
	v_lshl_add_u64 v[218:219], v[152:153], 1, s[46:47]
	v_lshl_add_u64 v[222:223], s[48:49], 0, v[154:155]
	v_lshl_add_u64 v[226:227], s[48:49], 0, v[156:157]
	global_load_dwordx4 v[210:213], v[210:211], off
	s_nop 0
	global_load_dwordx4 v[214:217], v[214:215], off
	s_nop 0
	global_load_dwordx4 v[218:221], v[218:219], off
	s_nop 0
	global_load_dwordx4 v[222:225], v[222:223], off
	s_nop 0
	global_load_dwordx4 v[226:229], v[226:227], off
	s_branch .LBB0_483
.LBB0_481:
	v_max_f32_e32 v0, v81, v81
	v_max_f32_e32 v14, v80, v80
	v_max_f32_e32 v0, v14, v0
	v_max3_f32 v0, v0, v82, v83
	v_max3_f32 v0, v0, v84, v85
	v_max3_f32 v0, v0, v86, v87
	v_max3_f32 v0, v0, v88, v89
	v_max3_f32 v0, v0, v90, v91
	v_max3_f32 v0, v0, v92, v93
	v_max3_f32 v0, v0, v94, v95
	v_max3_f32 v0, v0, v96, v97
	v_max3_f32 v0, v0, v98, v99
	v_max3_f32 v0, v0, v100, v101
	v_max3_f32 v0, v0, v102, v103
	v_and_b32_e32 v15, 64, v173
	v_max3_f32 v0, v0, v104, v105
	v_xor_b32_e32 v14, 32, v173
	v_add_u32_e32 v15, 64, v15
	v_max3_f32 v0, v0, v106, v107
	v_cmp_lt_i32_e32 vcc, v14, v15
	v_max3_f32 v0, v0, v108, v109
	v_max3_f32 v0, v0, v110, v111
	v_cndmask_b32_e32 v14, v173, v14, vcc
	v_lshlrev_b32_e32 v14, 2, v14
	ds_bpermute_b32 v14, v14, v0
	s_waitcnt lgkmcnt(0)
	v_max3_f32 v14, v193, v0, v14
	v_sub_f32_e32 v0, v80, v14
	v_exp_f32_e32 v80, v0
	v_sub_f32_e32 v0, v81, v14
	v_exp_f32_e32 v81, v0
	v_sub_f32_e32 v0, v193, v14
	v_sub_f32_e32 v82, v82, v14
	v_sub_f32_e32 v83, v83, v14
	v_sub_f32_e32 v84, v84, v14
	v_sub_f32_e32 v85, v85, v14
	v_sub_f32_e32 v86, v86, v14
	v_sub_f32_e32 v87, v87, v14
	v_add_u32_e32 v193, v191, v192
	v_exp_f32_e32 v82, v82
	v_exp_f32_e32 v83, v83
	v_exp_f32_e32 v84, v84
	v_exp_f32_e32 v85, v85
	v_exp_f32_e32 v86, v86
	v_exp_f32_e32 v87, v87
	v_exp_f32_e32 v0, v0
	ds_read_b64_tr_b16 v[194:195], v193 offset:38912
	ds_read_b64_tr_b16 v[196:197], v193 offset:40448
	ds_read_b64_tr_b16 v[204:205], v193 offset:40512
	ds_read_b64_tr_b16 v[202:203], v193 offset:38976
	v_add_f32_e32 v15, 0, v80
	v_add_f32_e32 v15, v81, v15
	v_mul_f32_e32 v30, v0, v30
	v_mul_f32_e32 v31, v0, v31
	v_mul_f32_e32 v28, v0, v28
	v_mul_f32_e32 v29, v0, v29
	v_mul_f32_e32 v26, v0, v26
	v_mul_f32_e32 v27, v0, v27
	v_mul_f32_e32 v24, v0, v24
	v_mul_f32_e32 v25, v0, v25
	v_mul_f32_e32 v22, v0, v22
	v_mul_f32_e32 v23, v0, v23
	v_mul_f32_e32 v20, v0, v20
	v_mul_f32_e32 v21, v0, v21
	v_mul_f32_e32 v18, v0, v18
	v_mul_f32_e32 v19, v0, v19
	v_mul_f32_e32 v16, v0, v16
	v_mul_f32_e32 v17, v0, v17
	v_mul_f32_e32 v46, v0, v46
	v_mul_f32_e32 v47, v0, v47
	v_mul_f32_e32 v44, v0, v44
	v_mul_f32_e32 v45, v0, v45
	v_mul_f32_e32 v42, v0, v42
	v_mul_f32_e32 v43, v0, v43
	v_cvt_pk_bf16_f32 v198, v80, v81
	v_cvt_pk_bf16_f32 v199, v82, v83
	v_cvt_pk_bf16_f32 v200, v84, v85
	v_cvt_pk_bf16_f32 v201, v86, v87
	v_mul_f32_e32 v40, v0, v40
	v_mul_f32_e32 v41, v0, v41
	v_mul_f32_e32 v38, v0, v38
	v_mul_f32_e32 v39, v0, v39
	v_mul_f32_e32 v36, v0, v36
	v_mul_f32_e32 v37, v0, v37
	v_mul_f32_e32 v34, v0, v34
	v_mul_f32_e32 v35, v0, v35
	v_mul_f32_e32 v32, v0, v32
	v_mul_f32_e32 v33, v0, v33
	v_add_f32_e32 v15, v82, v15
	s_waitcnt lgkmcnt(2)
	v_mfma_f32_32x32x16_bf16 v[16:31], v[194:197], v[198:201], v[16:31]
	v_add_f32_e32 v15, v83, v15
	v_sub_f32_e32 v88, v88, v14
	v_add_f32_e32 v15, v84, v15
	v_exp_f32_e32 v88, v88
	v_sub_f32_e32 v89, v89, v14
	v_sub_f32_e32 v90, v90, v14
	v_sub_f32_e32 v91, v91, v14
	s_waitcnt lgkmcnt(0)
	v_mfma_f32_32x32x16_bf16 v[32:47], v[202:205], v[198:201], v[32:47]
	v_sub_f32_e32 v92, v92, v14
	v_sub_f32_e32 v93, v93, v14
	v_sub_f32_e32 v94, v94, v14
	v_sub_f32_e32 v95, v95, v14
	v_add_f32_e32 v15, v85, v15
	v_exp_f32_e32 v89, v89
	v_exp_f32_e32 v90, v90
	v_exp_f32_e32 v91, v91
	v_exp_f32_e32 v92, v92
	v_exp_f32_e32 v93, v93
	v_exp_f32_e32 v94, v94
	v_exp_f32_e32 v95, v95
	ds_read_b64_tr_b16 v[194:195], v193 offset:41984
	ds_read_b64_tr_b16 v[196:197], v193 offset:43520
	ds_read_b64_tr_b16 v[204:205], v193 offset:43584
	ds_read_b64_tr_b16 v[202:203], v193 offset:42048
	v_add_f32_e32 v15, v86, v15
	v_add_f32_e32 v15, v87, v15
	v_add_f32_e32 v15, v88, v15
	v_add_f32_e32 v15, v89, v15
	v_cvt_pk_bf16_f32 v198, v88, v89
	v_cvt_pk_bf16_f32 v199, v90, v91
	v_cvt_pk_bf16_f32 v200, v92, v93
	v_cvt_pk_bf16_f32 v201, v94, v95
	v_add_f32_e32 v15, v90, v15
	v_add_f32_e32 v15, v91, v15
	s_waitcnt lgkmcnt(2)
	v_mfma_f32_32x32x16_bf16 v[16:31], v[194:197], v[198:201], v[16:31]
	v_sub_f32_e32 v96, v96, v14
	v_add_f32_e32 v15, v92, v15
	v_exp_f32_e32 v96, v96
	v_sub_f32_e32 v97, v97, v14
	v_sub_f32_e32 v98, v98, v14
	v_sub_f32_e32 v99, v99, v14
	v_sub_f32_e32 v100, v100, v14
	s_waitcnt lgkmcnt(0)
	v_mfma_f32_32x32x16_bf16 v[32:47], v[202:205], v[198:201], v[32:47]
	v_sub_f32_e32 v101, v101, v14
	v_sub_f32_e32 v102, v102, v14
	v_sub_f32_e32 v103, v103, v14
	v_add_f32_e32 v15, v93, v15
	v_exp_f32_e32 v97, v97
	v_exp_f32_e32 v98, v98
	v_exp_f32_e32 v99, v99
	v_exp_f32_e32 v100, v100
	v_exp_f32_e32 v101, v101
	v_exp_f32_e32 v102, v102
	v_exp_f32_e32 v103, v103
	ds_read_b64_tr_b16 v[194:195], v193 offset:45056
	ds_read_b64_tr_b16 v[196:197], v193 offset:46592
	ds_read_b64_tr_b16 v[204:205], v193 offset:46656
	ds_read_b64_tr_b16 v[202:203], v193 offset:45120
	v_add_f32_e32 v15, v94, v15
	v_add_f32_e32 v15, v95, v15
	v_add_f32_e32 v15, v96, v15
	v_add_f32_e32 v15, v97, v15
	v_cvt_pk_bf16_f32 v198, v96, v97
	v_cvt_pk_bf16_f32 v199, v98, v99
	v_cvt_pk_bf16_f32 v200, v100, v101
	v_cvt_pk_bf16_f32 v201, v102, v103
	v_add_f32_e32 v15, v98, v15
	v_add_f32_e32 v15, v99, v15
	s_waitcnt lgkmcnt(2)
	v_mfma_f32_32x32x16_bf16 v[16:31], v[194:197], v[198:201], v[16:31]
	v_sub_f32_e32 v104, v104, v14
	v_add_f32_e32 v15, v100, v15
	v_exp_f32_e32 v104, v104
	v_sub_f32_e32 v105, v105, v14
	v_sub_f32_e32 v106, v106, v14
	v_sub_f32_e32 v107, v107, v14
	v_sub_f32_e32 v108, v108, v14
	s_waitcnt lgkmcnt(0)
	v_mfma_f32_32x32x16_bf16 v[32:47], v[202:205], v[198:201], v[32:47]
	v_sub_f32_e32 v109, v109, v14
	v_sub_f32_e32 v110, v110, v14
	v_sub_f32_e32 v111, v111, v14
	v_add_f32_e32 v15, v101, v15
	v_exp_f32_e32 v105, v105
	v_exp_f32_e32 v106, v106
	v_exp_f32_e32 v107, v107
	v_exp_f32_e32 v108, v108
	v_exp_f32_e32 v109, v109
	v_exp_f32_e32 v110, v110
	ds_read_b64_tr_b16 v[194:195], v193 offset:48128
	ds_read_b64_tr_b16 v[196:197], v193 offset:49664
	v_exp_f32_e32 v111, v111
	ds_read_b64_tr_b16 v[204:205], v193 offset:49728
	ds_read_b64_tr_b16 v[202:203], v193 offset:48192
	v_add_f32_e32 v15, v102, v15
	v_add_f32_e32 v15, v103, v15
	v_add_f32_e32 v15, v104, v15
	v_cvt_pk_bf16_f32 v198, v104, v105
	v_cvt_pk_bf16_f32 v199, v106, v107
	v_cvt_pk_bf16_f32 v200, v108, v109
	v_cvt_pk_bf16_f32 v201, v110, v111
	v_add_f32_e32 v15, v105, v15
	v_add_f32_e32 v15, v106, v15
	s_waitcnt lgkmcnt(2)
	v_mfma_f32_32x32x16_bf16 v[16:31], v[194:197], v[198:201], v[16:31]
	v_add_f32_e32 v15, v107, v15
	v_add_f32_e32 v15, v108, v15
	v_add_f32_e32 v15, v109, v15
	v_add_f32_e32 v15, v110, v15
	v_add_f32_e32 v15, v111, v15
	v_fmac_f32_e32 v15, v190, v0
	v_mov_b32_e32 v193, v14
	s_waitcnt lgkmcnt(0)
	v_mfma_f32_32x32x16_bf16 v[32:47], v[202:205], v[198:201], v[32:47]
	v_mov_b32_e32 v190, v15
.LBB0_482:
	s_add_i32 s40, s40, 2
	s_addk_i32 s41, 0x80
	s_cmp_lt_i32 s44, s15
	s_waitcnt vmcnt(9)
	ds_write_b128 v186, v[2:5] offset:13312
	s_waitcnt vmcnt(8)
	ds_write_b128 v187, v[6:9] offset:13312
	s_waitcnt vmcnt(7)
	ds_write_b128 v188, v[10:13] offset:13312
	s_waitcnt vmcnt(6)
	ds_write_b128 v158, v[136:139] offset:26624
	s_waitcnt vmcnt(5)
	ds_write_b128 v158, v[140:143] offset:32768
	s_waitcnt lgkmcnt(0)
	s_barrier
	s_cbranch_scc0 .LBB0_389
.LBB0_483:
	s_add_i32 s44, s40, -1
	s_cmp_ge_i32 s44, s15
	s_cselect_b64 s[0:1], -1, 0
	s_cselect_b32 s16, 0, s44
	s_add_i32 s45, s40, -2
	s_cmp_ge_i32 s45, s15
	s_cselect_b64 s[46:47], -1, 0
	s_cmp_lt_i32 s40, s15
	s_cselect_b32 s100, s40, 0
	s_mul_hi_u32 s51, s100, 0x3000
	s_mul_i32 s50, s100, 0x3000
	s_add_u32 s50, s6, s50
	s_addc_u32 s51, s7, s51
	s_lshl_b64 s[98:99], s[16:17], 13
	s_add_u32 s98, s8, s98
	s_addc_u32 s99, s9, s99
	v_lshl_add_u64 v[2:3], s[50:51], 0, v[154:155]
	v_lshl_add_u64 v[6:7], s[50:51], 0, v[156:157]
	v_lshl_add_u64 v[10:11], v[152:153], 1, s[50:51]
	v_lshl_add_u64 v[136:137], s[98:99], 0, v[154:155]
	v_lshl_add_u64 v[140:141], s[98:99], 0, v[156:157]
	s_add_i32 s45, s41, 0xffffffa2
	s_cmp_gt_i32 s45, s14
	s_cselect_b64 s[48:49], -1, 0
	s_or_b64 s[46:47], s[46:47], s[48:49]
	s_and_b64 vcc, exec, s[46:47]
	s_cbranch_vccnz .LldA
	ds_read_b128 v[80:83], v159 offset:13312
	ds_read_b128 v[194:197], v159 offset:13344
	ds_read_b128 v[96:99], v159 offset:19968
	ds_read_b128 v[230:233], v159 offset:20000
	ds_read_b128 v[234:237], v159 offset:13376
	s_waitcnt lgkmcnt(4)
	v_mfma_f32_32x32x16_bf16 v[80:95], v[80:83], v[112:115], 0
	s_waitcnt lgkmcnt(3)
	v_mfma_f32_32x32x16_bf16 v[80:95], v[194:197], v[116:119], v[80:95]
	global_load_dwordx4 v[2:5], v[2:3], off
	ds_read_b128 v[194:197], v159 offset:20032
	s_waitcnt lgkmcnt(3)
	v_mfma_f32_32x32x16_bf16 v[96:111], v[96:99], v[112:115], 0
	s_waitcnt lgkmcnt(2)
	v_mfma_f32_32x32x16_bf16 v[96:111], v[230:233], v[116:119], v[96:111]
	global_load_dwordx4 v[6:9], v[6:7], off
	ds_read_b128 v[230:233], v159 offset:13408
	s_waitcnt lgkmcnt(2)
	v_mfma_f32_32x32x16_bf16 v[80:95], v[234:237], v[120:123], v[80:95]
	ds_read_b128 v[234:237], v159 offset:20064
	s_waitcnt lgkmcnt(2)
	v_mfma_f32_32x32x16_bf16 v[96:111], v[194:197], v[120:123], v[96:111]
	global_load_dwordx4 v[10:13], v[10:11], off
	ds_read_b128 v[194:197], v159 offset:13440
	s_waitcnt lgkmcnt(2)
	v_mfma_f32_32x32x16_bf16 v[80:95], v[230:233], v[124:127], v[80:95]
	ds_read_b128 v[230:233], v159 offset:20096
	s_waitcnt lgkmcnt(2)
	v_mfma_f32_32x32x16_bf16 v[96:111], v[234:237], v[124:127], v[96:111]
	global_load_dwordx4 v[136:139], v[136:137], off
	ds_read_b128 v[234:237], v159 offset:13472
	s_waitcnt lgkmcnt(2)
	v_mfma_f32_32x32x16_bf16 v[80:95], v[194:197], v[128:131], v[80:95]
	ds_read_b128 v[194:197], v159 offset:20128
	s_waitcnt lgkmcnt(2)
	v_mfma_f32_32x32x16_bf16 v[96:111], v[230:233], v[128:131], v[96:111]
	global_load_dwordx4 v[140:143], v[140:141], off
	s_waitcnt lgkmcnt(1)
	v_mfma_f32_32x32x16_bf16 v[80:95], v[234:237], v[132:135], v[80:95]
	s_waitcnt lgkmcnt(0)
	v_mfma_f32_32x32x16_bf16 v[96:111], v[194:197], v[132:135], v[96:111]

.LBB0_488:
	v_max_f32_e32 v0, v49, v49
	v_max_f32_e32 v14, v48, v48
	v_max_f32_e32 v0, v14, v0
	v_max3_f32 v0, v0, v50, v51
	v_max3_f32 v0, v0, v52, v53
	v_max3_f32 v0, v0, v54, v55
	v_max3_f32 v0, v0, v56, v57
	v_max3_f32 v0, v0, v58, v59
	v_max3_f32 v0, v0, v60, v61
	v_max3_f32 v0, v0, v62, v63
	v_max3_f32 v0, v0, v64, v65
	v_max3_f32 v0, v0, v66, v67
	v_max3_f32 v0, v0, v68, v69
	v_max3_f32 v0, v0, v70, v71
	v_and_b32_e32 v15, 64, v173
	v_max3_f32 v0, v0, v72, v73
	v_xor_b32_e32 v14, 32, v173
	v_add_u32_e32 v15, 64, v15
	v_max3_f32 v0, v0, v74, v75
	v_cmp_lt_i32_e32 vcc, v14, v15
	v_max3_f32 v0, v0, v76, v77
	v_max3_f32 v0, v0, v78, v79
	v_cndmask_b32_e32 v14, v173, v14, vcc
	v_lshlrev_b32_e32 v14, 2, v14
	ds_bpermute_b32 v14, v14, v0
	s_waitcnt lgkmcnt(0)
	v_max3_f32 v14, v193, v0, v14
	v_sub_f32_e32 v0, v48, v14
	v_exp_f32_e32 v48, v0
	v_sub_f32_e32 v0, v49, v14
	v_exp_f32_e32 v49, v0
	v_sub_f32_e32 v0, v193, v14
	v_sub_f32_e32 v50, v50, v14
	v_sub_f32_e32 v51, v51, v14
	v_sub_f32_e32 v52, v52, v14
	v_sub_f32_e32 v53, v53, v14
	v_sub_f32_e32 v54, v54, v14
	v_sub_f32_e32 v55, v55, v14
	v_add_u32_e32 v193, v191, v192
	v_exp_f32_e32 v50, v50
	v_exp_f32_e32 v51, v51
	v_exp_f32_e32 v52, v52
	v_exp_f32_e32 v53, v53
	v_exp_f32_e32 v54, v54
	v_exp_f32_e32 v55, v55
	v_exp_f32_e32 v0, v0
	ds_read_b64_tr_b16 v[194:195], v193 offset:26624
	ds_read_b64_tr_b16 v[196:197], v193 offset:28160
	ds_read_b64_tr_b16 v[204:205], v193 offset:28224
	ds_read_b64_tr_b16 v[202:203], v193 offset:26688
	v_add_f32_e32 v15, 0, v48
	v_add_f32_e32 v15, v49, v15
	v_mul_f32_e32 v30, v0, v30
	v_mul_f32_e32 v31, v0, v31
	v_mul_f32_e32 v28, v0, v28
	v_mul_f32_e32 v29, v0, v29
	v_mul_f32_e32 v26, v0, v26
	v_mul_f32_e32 v27, v0, v27
	v_mul_f32_e32 v24, v0, v24
	v_mul_f32_e32 v25, v0, v25
	v_mul_f32_e32 v22, v0, v22
	v_mul_f32_e32 v23, v0, v23
	v_mul_f32_e32 v20, v0, v20
	v_mul_f32_e32 v21, v0, v21
	v_mul_f32_e32 v18, v0, v18
	v_mul_f32_e32 v19, v0, v19
	v_mul_f32_e32 v16, v0, v16
	v_mul_f32_e32 v17, v0, v17
	v_mul_f32_e32 v46, v0, v46
	v_mul_f32_e32 v47, v0, v47
	v_mul_f32_e32 v44, v0, v44
	v_mul_f32_e32 v45, v0, v45
	v_mul_f32_e32 v42, v0, v42
	v_mul_f32_e32 v43, v0, v43
	v_cvt_pk_bf16_f32 v198, v48, v49
	v_cvt_pk_bf16_f32 v199, v50, v51
	v_cvt_pk_bf16_f32 v200, v52, v53
	v_cvt_pk_bf16_f32 v201, v54, v55
	v_mul_f32_e32 v40, v0, v40
	v_mul_f32_e32 v41, v0, v41
	v_mul_f32_e32 v38, v0, v38
	v_mul_f32_e32 v39, v0, v39
	v_mul_f32_e32 v36, v0, v36
	v_mul_f32_e32 v37, v0, v37
	v_mul_f32_e32 v34, v0, v34
	v_mul_f32_e32 v35, v0, v35
	v_mul_f32_e32 v32, v0, v32
	v_mul_f32_e32 v33, v0, v33
	v_add_f32_e32 v15, v50, v15
	s_waitcnt lgkmcnt(2)
	v_mfma_f32_32x32x16_bf16 v[16:31], v[194:197], v[198:201], v[16:31]
	v_add_f32_e32 v15, v51, v15
	v_sub_f32_e32 v56, v56, v14
	v_add_f32_e32 v15, v52, v15
	v_exp_f32_e32 v56, v56
	v_sub_f32_e32 v57, v57, v14
	v_sub_f32_e32 v58, v58, v14
	v_sub_f32_e32 v59, v59, v14
	s_waitcnt lgkmcnt(0)
	v_mfma_f32_32x32x16_bf16 v[32:47], v[202:205], v[198:201], v[32:47]
	v_sub_f32_e32 v60, v60, v14
	v_sub_f32_e32 v61, v61, v14
	v_sub_f32_e32 v62, v62, v14
	v_sub_f32_e32 v63, v63, v14
	v_add_f32_e32 v15, v53, v15
	v_exp_f32_e32 v57, v57
	v_exp_f32_e32 v58, v58
	v_exp_f32_e32 v59, v59
	v_exp_f32_e32 v60, v60
	v_exp_f32_e32 v61, v61
	v_exp_f32_e32 v62, v62
	v_exp_f32_e32 v63, v63
	ds_read_b64_tr_b16 v[194:195], v193 offset:29696
	ds_read_b64_tr_b16 v[196:197], v193 offset:31232
	ds_read_b64_tr_b16 v[204:205], v193 offset:31296
	ds_read_b64_tr_b16 v[202:203], v193 offset:29760
	v_add_f32_e32 v15, v54, v15
	v_add_f32_e32 v15, v55, v15
	v_add_f32_e32 v15, v56, v15
	v_add_f32_e32 v15, v57, v15
	v_cvt_pk_bf16_f32 v198, v56, v57
	v_cvt_pk_bf16_f32 v199, v58, v59
	v_cvt_pk_bf16_f32 v200, v60, v61
	v_cvt_pk_bf16_f32 v201, v62, v63
	v_add_f32_e32 v15, v58, v15
	v_add_f32_e32 v15, v59, v15
	s_waitcnt lgkmcnt(2)
	v_mfma_f32_32x32x16_bf16 v[16:31], v[194:197], v[198:201], v[16:31]
	v_sub_f32_e32 v64, v64, v14
	v_add_f32_e32 v15, v60, v15
	v_exp_f32_e32 v64, v64
	v_sub_f32_e32 v65, v65, v14
	v_sub_f32_e32 v66, v66, v14
	v_sub_f32_e32 v67, v67, v14
	v_sub_f32_e32 v68, v68, v14
	s_waitcnt lgkmcnt(0)
	v_mfma_f32_32x32x16_bf16 v[32:47], v[202:205], v[198:201], v[32:47]
	v_sub_f32_e32 v69, v69, v14
	v_sub_f32_e32 v70, v70, v14
	v_sub_f32_e32 v71, v71, v14
	v_add_f32_e32 v15, v61, v15
	v_exp_f32_e32 v65, v65
	v_exp_f32_e32 v66, v66
	v_exp_f32_e32 v67, v67
	v_exp_f32_e32 v68, v68
	v_exp_f32_e32 v69, v69
	v_exp_f32_e32 v70, v70
	v_exp_f32_e32 v71, v71
	ds_read_b64_tr_b16 v[194:195], v193 offset:32768
	ds_read_b64_tr_b16 v[196:197], v193 offset:34304
	ds_read_b64_tr_b16 v[204:205], v193 offset:34368
	ds_read_b64_tr_b16 v[202:203], v193 offset:32832
	v_add_f32_e32 v15, v62, v15
	v_add_f32_e32 v15, v63, v15
	v_add_f32_e32 v15, v64, v15
	v_add_f32_e32 v15, v65, v15
	v_cvt_pk_bf16_f32 v198, v64, v65
	v_cvt_pk_bf16_f32 v199, v66, v67
	v_cvt_pk_bf16_f32 v200, v68, v69
	v_cvt_pk_bf16_f32 v201, v70, v71
	v_add_f32_e32 v15, v66, v15
	v_add_f32_e32 v15, v67, v15
	s_waitcnt lgkmcnt(2)
	v_mfma_f32_32x32x16_bf16 v[16:31], v[194:197], v[198:201], v[16:31]
	v_sub_f32_e32 v72, v72, v14
	v_add_f32_e32 v15, v68, v15
	v_exp_f32_e32 v72, v72
	v_sub_f32_e32 v73, v73, v14
	v_sub_f32_e32 v74, v74, v14
	v_sub_f32_e32 v75, v75, v14
	v_sub_f32_e32 v76, v76, v14
	s_waitcnt lgkmcnt(0)
	v_mfma_f32_32x32x16_bf16 v[32:47], v[202:205], v[198:201], v[32:47]
	v_sub_f32_e32 v77, v77, v14
	v_sub_f32_e32 v78, v78, v14
	v_sub_f32_e32 v79, v79, v14
	v_add_f32_e32 v15, v69, v15
	v_exp_f32_e32 v73, v73
	v_exp_f32_e32 v74, v74
	v_exp_f32_e32 v75, v75
	v_exp_f32_e32 v76, v76
	v_exp_f32_e32 v77, v77
	v_exp_f32_e32 v78, v78
	ds_read_b64_tr_b16 v[194:195], v193 offset:35840
	ds_read_b64_tr_b16 v[196:197], v193 offset:37376
	v_exp_f32_e32 v79, v79
	ds_read_b64_tr_b16 v[204:205], v193 offset:37440
	ds_read_b64_tr_b16 v[202:203], v193 offset:35904
	v_add_f32_e32 v15, v70, v15
	v_add_f32_e32 v15, v71, v15
	v_add_f32_e32 v15, v72, v15
	v_cvt_pk_bf16_f32 v198, v72, v73
	v_cvt_pk_bf16_f32 v199, v74, v75
	v_cvt_pk_bf16_f32 v200, v76, v77
	v_cvt_pk_bf16_f32 v201, v78, v79
	v_add_f32_e32 v15, v73, v15
	v_add_f32_e32 v15, v74, v15
	s_waitcnt lgkmcnt(2)
	v_mfma_f32_32x32x16_bf16 v[16:31], v[194:197], v[198:201], v[16:31]
	v_add_f32_e32 v15, v75, v15
	v_add_f32_e32 v15, v76, v15
	v_add_f32_e32 v15, v77, v15
	v_add_f32_e32 v15, v78, v15
	v_add_f32_e32 v15, v79, v15
	v_fmac_f32_e32 v15, v190, v0
	v_mov_b32_e32 v193, v14
	s_waitcnt lgkmcnt(0)
	v_mfma_f32_32x32x16_bf16 v[32:47], v[202:205], v[198:201], v[32:47]
	v_mov_b32_e32 v190, v15
.LBB0_489:
	s_add_i32 s100, s40, 1
	s_cmp_lt_i32 s100, s15
	s_cselect_b32 s100, s100, 0
	s_mul_hi_u32 s47, s100, 0x3000
	s_mul_i32 s46, s100, 0x3000
	s_add_u32 s46, s6, s46
	s_addc_u32 s47, s7, s47
	s_cmp_lt_i32 s40, s15
	s_cselect_b32 s48, s40, 0
	s_mov_b32 s49, 0
	s_lshl_b64 s[48:49], s[48:49], 13
	s_add_u32 s48, s8, s48
	s_addc_u32 s49, s9, s49
	s_waitcnt vmcnt(9)
	ds_write_b128 v186, v[210:213]
	s_waitcnt vmcnt(8)
	ds_write_b128 v187, v[214:217]
	s_waitcnt vmcnt(7)
	ds_write_b128 v188, v[218:221]
	s_waitcnt vmcnt(6)
	ds_write_b128 v158, v[222:225] offset:38912
	s_waitcnt vmcnt(5)
	ds_write_b128 v158, v[226:229] offset:45056
	v_lshl_add_u64 v[210:211], s[46:47], 0, v[154:155]
	v_lshl_add_u64 v[214:215], s[46:47], 0, v[156:157]
	v_lshl_add_u64 v[218:219], v[152:153], 1, s[46:47]
	v_lshl_add_u64 v[222:223], s[48:49], 0, v[154:155]
	v_lshl_add_u64 v[226:227], s[48:49], 0, v[156:157]
	s_waitcnt lgkmcnt(0)
	s_barrier
	s_sub_i32 s16, s41, 30
	s_cmp_gt_i32 s16, s14
	s_cselect_b64 s[46:47], -1, 0
	s_or_b64 s[0:1], s[0:1], s[46:47]
	s_and_b64 vcc, exec, s[0:1]
	s_cbranch_vccnz .LldB
	ds_read_b128 v[48:51], v159
	ds_read_b128 v[194:197], v159 offset:32
	ds_read_b128 v[64:67], v159 offset:6656
	ds_read_b128 v[230:233], v159 offset:6688
	ds_read_b128 v[234:237], v159 offset:64
	s_waitcnt lgkmcnt(4)
	v_mfma_f32_32x32x16_bf16 v[48:63], v[48:51], v[112:115], 0
	s_waitcnt lgkmcnt(3)
	v_mfma_f32_32x32x16_bf16 v[48:63], v[194:197], v[116:119], v[48:63]
	global_load_dwordx4 v[210:213], v[210:211], off
	ds_read_b128 v[194:197], v159 offset:6720
	s_waitcnt lgkmcnt(3)
	v_mfma_f32_32x32x16_bf16 v[64:79], v[64:67], v[112:115], 0
	s_waitcnt lgkmcnt(2)
	v_mfma_f32_32x32x16_bf16 v[64:79], v[230:233], v[116:119], v[64:79]
	global_load_dwordx4 v[214:217], v[214:215], off
	ds_read_b128 v[230:233], v159 offset:96
	s_waitcnt lgkmcnt(2)
	v_mfma_f32_32x32x16_bf16 v[48:63], v[234:237], v[120:123], v[48:63]
	ds_read_b128 v[234:237], v159 offset:6752
	s_waitcnt lgkmcnt(2)
	v_mfma_f32_32x32x16_bf16 v[64:79], v[194:197], v[120:123], v[64:79]
	global_load_dwordx4 v[218:221], v[218:219], off
	ds_read_b128 v[194:197], v159 offset:128
	s_waitcnt lgkmcnt(2)
	v_mfma_f32_32x32x16_bf16 v[48:63], v[230:233], v[124:127], v[48:63]
	ds_read_b128 v[230:233], v159 offset:6784
	s_waitcnt lgkmcnt(2)
	v_mfma_f32_32x32x16_bf16 v[64:79], v[234:237], v[124:127], v[64:79]
	global_load_dwordx4 v[222:225], v[222:223], off
	ds_read_b128 v[234:237], v159 offset:160
	s_waitcnt lgkmcnt(2)
	v_mfma_f32_32x32x16_bf16 v[48:63], v[194:197], v[128:131], v[48:63]
	ds_read_b128 v[194:197], v159 offset:6816
	s_waitcnt lgkmcnt(2)
	v_mfma_f32_32x32x16_bf16 v[64:79], v[230:233], v[128:131], v[64:79]
	global_load_dwordx4 v[226:229], v[226:227], off
	s_waitcnt lgkmcnt(1)
	v_mfma_f32_32x32x16_bf16 v[48:63], v[234:237], v[132:135], v[48:63]
	s_waitcnt lgkmcnt(0)
	v_mfma_f32_32x32x16_bf16 v[64:79], v[194:197], v[132:135], v[64:79]

.LldA:
	global_load_dwordx4 v[2:5], v[2:3], off
	global_load_dwordx4 v[6:9], v[6:7], off
	global_load_dwordx4 v[10:13], v[10:11], off
	global_load_dwordx4 v[136:139], v[136:137], off
	global_load_dwordx4 v[140:143], v[140:141], off
	s_branch .LBB0_485
.LldB:
	global_load_dwordx4 v[210:213], v[210:211], off
	global_load_dwordx4 v[214:217], v[214:215], off
	global_load_dwordx4 v[218:221], v[218:219], off
	global_load_dwordx4 v[222:225], v[222:223], off
	global_load_dwordx4 v[226:229], v[226:227], off
	s_branch .LBB0_491

	.amdhsa_kernel _Z14fwd_megakernel6Params
		.amdhsa_group_segment_fixed_size 78368
		.amdhsa_private_segment_fixed_size 0
		.amdhsa_kernarg_size 440
		.amdhsa_user_sgpr_count 2
		.amdhsa_user_sgpr_dispatch_ptr 0
		.amdhsa_user_sgpr_queue_ptr 0
		.amdhsa_user_sgpr_kernarg_segment_ptr 1
		.amdhsa_user_sgpr_dispatch_id 0
		.amdhsa_user_sgpr_kernarg_preload_length 0
		.amdhsa_user_sgpr_kernarg_preload_offset 0
		.amdhsa_user_sgpr_private_segment_size 0
		.amdhsa_uses_dynamic_stack 0
		.amdhsa_enable_private_segment 0
		.amdhsa_system_sgpr_workgroup_id_x 1
		.amdhsa_system_sgpr_workgroup_id_y 0
		.amdhsa_system_sgpr_workgroup_id_z 0
		.amdhsa_system_sgpr_workgroup_info 0
		.amdhsa_system_vgpr_workitem_id 2
		.amdhsa_next_free_vgpr 238
		.amdhsa_next_free_sgpr 101
		.amdhsa_accum_offset 240
		.amdhsa_reserve_vcc 1
		.amdhsa_float_round_mode_32 0
		.amdhsa_float_round_mode_16_64 0
		.amdhsa_float_denorm_mode_32 3
		.amdhsa_float_denorm_mode_16_64 3
		.amdhsa_dx10_clamp 1
		.amdhsa_ieee_mode 1
		.amdhsa_fp16_overflow 0
		.amdhsa_tg_split 0
		.amdhsa_exception_fp_ieee_invalid_op 0
		.amdhsa_exception_fp_denorm_src 0
		.amdhsa_exception_fp_ieee_div_zero 0
		.amdhsa_exception_fp_ieee_overflow 0
		.amdhsa_exception_fp_ieee_underflow 0
		.amdhsa_exception_fp_ieee_inexact 0
		.amdhsa_exception_int_div_zero 0
	.end_amdhsa_kernel

amdhsa.kernels:
  - .agpr_count:     0
    .args:
      - .offset:         0
        .size:           184
        .value_kind:     by_value
      - .offset:         184
        .size:           4
        .value_kind:     hidden_block_count_x
      - .offset:         188
        .size:           4
        .value_kind:     hidden_block_count_y
      - .offset:         192
        .size:           4
        .value_kind:     hidden_block_count_z
      - .offset:         196
        .size:           2
        .value_kind:     hidden_group_size_x
      - .offset:         198
        .size:           2
        .value_kind:     hidden_group_size_y
      - .offset:         200
        .size:           2
        .value_kind:     hidden_group_size_z
      - .offset:         202
        .size:           2
        .value_kind:     hidden_remainder_x
      - .offset:         204
        .size:           2
        .value_kind:     hidden_remainder_y
      - .offset:         206
        .size:           2
        .value_kind:     hidden_remainder_z
      - .offset:         224
        .size:           8
        .value_kind:     hidden_global_offset_x
      - .offset:         232
        .size:           8
        .value_kind:     hidden_global_offset_y
      - .offset:         240
        .size:           8
        .value_kind:     hidden_global_offset_z
      - .offset:         248
        .size:           2
        .value_kind:     hidden_grid_dims
      - .offset:         272
        .size:           8
        .value_kind:     hidden_multigrid_sync_arg
    .group_segment_fixed_size: 78368
    .kernarg_segment_align: 8
    .kernarg_segment_size: 440
    .language:       OpenCL C
    .language_version:
      - 2
      - 0
    .max_flat_workgroup_size: 256
    .name:           _Z14fwd_megakernel6Params
    .private_segment_fixed_size: 0
    .sgpr_count:     107
    .sgpr_spill_count: 165
    .symbol:         _Z14fwd_megakernel6Params.kd
    .uniform_work_group_size: 1
    .uses_dynamic_stack: false
    .vgpr_count:     238
    .vgpr_spill_count: 0
    .wavefront_size: 64
